# P2 loop phases 1 and 3: issue the A-tile (HBM) LDS-DMA loads before the ds_reads and the B-tile loads after them
# speedup vs baseline: 1.0074x; 1.0054x over previous
.LBB0_325:
	ds_read_b128 v[152:155], v149
	ds_read_b128 v[156:159], v149 offset:1024
	ds_read_b128 v[160:163], v149 offset:2048
	ds_read_b128 v[164:167], v149 offset:3072
	ds_read_b128 v[168:171], v150
	ds_read_b128 v[172:175], v150 offset:1024
	ds_read_b128 v[176:179], v150 offset:2048
	ds_read_b128 v[180:183], v150 offset:3072
	s_add_u32 s50, s46, 0x10000
	s_addc_u32 s51, s47, 0
	s_cmp_eq_u32 s91, 40
	s_cselect_b32 s55, s5, s51
	s_cselect_b32 s54, s4, s50
	s_cselect_b32 s53, s43, s90
	s_cselect_b32 s52, s42, s89
	v_lshl_add_u64 v[144:145], s[46:47], 0, v[136:137]
	s_add_i32 m0, s35, 0xc000
	ds_read_b128 v[184:187], v151
	ds_read_b128 v[190:193], v151 offset:1024
	ds_read_b128 v[194:197], v151 offset:2048
	ds_read_b128 v[198:201], v151 offset:3072
	ds_read_b128 v[202:205], v151 offset:4096
	ds_read_b128 v[206:209], v151 offset:5120
	ds_read_b128 v[210:213], v151 offset:6144
	ds_read_b128 v[214:217], v151 offset:7168
	global_load_lds_dwordx4 v[144:145], off
	v_lshl_add_u64 v[144:145], s[46:47], 0, v[138:139]
	s_add_i32 m0, s35, 0xe000
	s_nop 0
	global_load_lds_dwordx4 v[144:145], off
	s_waitcnt vmcnt(8)
	s_waitcnt lgkmcnt(0)
	s_barrier
	s_waitcnt lgkmcnt(0)
	v_mfma_f32_16x16x32_bf16 v[124:127], v[152:155], v[184:187], v[124:127]
	v_mfma_f32_16x16x32_bf16 v[120:123], v[160:163], v[184:187], v[120:123]
	v_mfma_f32_16x16x32_bf16 v[116:119], v[152:155], v[194:197], v[116:119]
	v_mfma_f32_16x16x32_bf16 v[108:111], v[160:163], v[194:197], v[108:111]
	v_mfma_f32_16x16x32_bf16 v[100:103], v[152:155], v[202:205], v[100:103]
	v_mfma_f32_16x16x32_bf16 v[92:95], v[160:163], v[202:205], v[92:95]
	v_mfma_f32_16x16x32_bf16 v[84:87], v[152:155], v[210:213], v[84:87]
	v_mfma_f32_16x16x32_bf16 v[76:79], v[160:163], v[210:213], v[76:79]
	v_mfma_f32_16x16x32_bf16 v[124:127], v[156:159], v[190:193], v[124:127]
	v_mfma_f32_16x16x32_bf16 v[120:123], v[164:167], v[190:193], v[120:123]
	v_mfma_f32_16x16x32_bf16 v[116:119], v[156:159], v[198:201], v[116:119]
	v_mfma_f32_16x16x32_bf16 v[108:111], v[164:167], v[198:201], v[108:111]
	v_mfma_f32_16x16x32_bf16 v[100:103], v[156:159], v[206:209], v[100:103]
	v_mfma_f32_16x16x32_bf16 v[92:95], v[164:167], v[206:209], v[92:95]
	v_mfma_f32_16x16x32_bf16 v[84:87], v[156:159], v[214:217], v[84:87]
	v_mfma_f32_16x16x32_bf16 v[76:79], v[164:167], v[214:217], v[76:79]
	v_mfma_f32_16x16x32_bf16 v[112:115], v[168:171], v[184:187], v[112:115]
	v_mfma_f32_16x16x32_bf16 v[104:107], v[176:179], v[184:187], v[104:107]
	v_mfma_f32_16x16x32_bf16 v[96:99], v[168:171], v[194:197], v[96:99]
	v_mfma_f32_16x16x32_bf16 v[88:91], v[176:179], v[194:197], v[88:91]
	v_mfma_f32_16x16x32_bf16 v[80:83], v[168:171], v[202:205], v[80:83]
	v_mfma_f32_16x16x32_bf16 v[72:75], v[176:179], v[202:205], v[72:75]
	v_mfma_f32_16x16x32_bf16 v[68:71], v[168:171], v[210:213], v[68:71]
	v_mfma_f32_16x16x32_bf16 v[64:67], v[176:179], v[210:213], v[64:67]
	v_mfma_f32_16x16x32_bf16 v[112:115], v[172:175], v[190:193], v[112:115]
	v_mfma_f32_16x16x32_bf16 v[104:107], v[180:183], v[190:193], v[104:107]
	v_mfma_f32_16x16x32_bf16 v[96:99], v[172:175], v[198:201], v[96:99]
	v_mfma_f32_16x16x32_bf16 v[88:91], v[180:183], v[198:201], v[88:91]
	v_mfma_f32_16x16x32_bf16 v[80:83], v[172:175], v[206:209], v[80:83]
	v_mfma_f32_16x16x32_bf16 v[72:75], v[180:183], v[206:209], v[72:75]
	v_mfma_f32_16x16x32_bf16 v[68:71], v[172:175], v[214:217], v[68:71]
	v_mfma_f32_16x16x32_bf16 v[64:67], v[180:183], v[214:217], v[64:67]
	s_barrier
	v_lshl_add_u64 v[220:221], s[54:55], 0, v[128:129]
	s_mov_b32 m0, s35
	v_lshl_add_u64 v[222:223], s[54:55], 0, v[132:133]
	global_load_lds_dwordx4 v[220:221], off
	s_mov_b32 m0, s60
	s_nop 0
	global_load_lds_dwordx4 v[222:223], off
	ds_read_b128 v[184:187], v151 offset:16384
	ds_read_b128 v[190:193], v151 offset:17408
	ds_read_b128 v[194:197], v151 offset:18432
	ds_read_b128 v[198:201], v151 offset:19456
	ds_read_b128 v[202:205], v151 offset:20480
	ds_read_b128 v[206:209], v151 offset:21504
	ds_read_b128 v[210:213], v151 offset:22528
	ds_read_b128 v[214:217], v151 offset:23552
	s_add_i32 s28, s76, s34
	v_lshl_add_u64 v[144:145], s[52:53], 0, v[130:131]
	s_mov_b32 m0, s28
	s_nop 0
	global_load_lds_dwordx4 v[144:145], off
	s_add_i32 m0, s28, 0x2000
	s_add_u32 s28, s52, 0xb0000
	v_lshl_add_u64 v[218:219], s[52:53], 0, v[134:135]
	s_addc_u32 s29, s53, 0
	s_add_i32 s33, s77, s34
	global_load_lds_dwordx4 v[218:219], off
	v_lshl_add_u64 v[224:225], s[28:29], 0, v[130:131]
	s_mov_b32 m0, s33
	s_nop 0
	global_load_lds_dwordx4 v[224:225], off
	v_lshl_add_u64 v[224:225], s[28:29], 0, v[134:135]
	s_add_i32 m0, s33, 0x2000
	s_nop 0
	global_load_lds_dwordx4 v[224:225], off
	s_waitcnt vmcnt(8)
	s_waitcnt lgkmcnt(0)
	s_barrier
	s_waitcnt lgkmcnt(0)
	v_mfma_f32_16x16x32_bf16 v[60:63], v[152:155], v[184:187], v[60:63]
	v_mfma_f32_16x16x32_bf16 v[56:59], v[160:163], v[184:187], v[56:59]
	v_mfma_f32_16x16x32_bf16 v[52:55], v[152:155], v[194:197], v[52:55]
	v_mfma_f32_16x16x32_bf16 v[44:47], v[160:163], v[194:197], v[44:47]
	v_mfma_f32_16x16x32_bf16 v[36:39], v[152:155], v[202:205], v[36:39]
	v_mfma_f32_16x16x32_bf16 v[28:31], v[160:163], v[202:205], v[28:31]
	v_mfma_f32_16x16x32_bf16 v[20:23], v[152:155], v[210:213], v[20:23]
	v_mfma_f32_16x16x32_bf16 v[12:15], v[160:163], v[210:213], v[12:15]
	v_mfma_f32_16x16x32_bf16 v[60:63], v[156:159], v[190:193], v[60:63]
	v_mfma_f32_16x16x32_bf16 v[56:59], v[164:167], v[190:193], v[56:59]
	v_mfma_f32_16x16x32_bf16 v[52:55], v[156:159], v[198:201], v[52:55]
	v_mfma_f32_16x16x32_bf16 v[44:47], v[164:167], v[198:201], v[44:47]
	v_mfma_f32_16x16x32_bf16 v[36:39], v[156:159], v[206:209], v[36:39]
	v_mfma_f32_16x16x32_bf16 v[28:31], v[164:167], v[206:209], v[28:31]
	v_mfma_f32_16x16x32_bf16 v[20:23], v[156:159], v[214:217], v[20:23]
	v_mfma_f32_16x16x32_bf16 v[12:15], v[164:167], v[214:217], v[12:15]
	v_mfma_f32_16x16x32_bf16 v[48:51], v[168:171], v[184:187], v[48:51]
	v_mfma_f32_16x16x32_bf16 v[40:43], v[176:179], v[184:187], v[40:43]
	v_mfma_f32_16x16x32_bf16 v[32:35], v[168:171], v[194:197], v[32:35]
	v_mfma_f32_16x16x32_bf16 v[24:27], v[176:179], v[194:197], v[24:27]
	v_mfma_f32_16x16x32_bf16 v[16:19], v[168:171], v[202:205], v[16:19]
	v_mfma_f32_16x16x32_bf16 v[8:11], v[176:179], v[202:205], v[8:11]
	v_mfma_f32_16x16x32_bf16 v[4:7], v[168:171], v[210:213], v[4:7]
	v_mfma_f32_16x16x32_bf16 v[0:3], v[176:179], v[210:213], v[0:3]
	v_mfma_f32_16x16x32_bf16 v[48:51], v[172:175], v[190:193], v[48:51]
	v_mfma_f32_16x16x32_bf16 v[40:43], v[180:183], v[190:193], v[40:43]
	v_mfma_f32_16x16x32_bf16 v[32:35], v[172:175], v[198:201], v[32:35]
	v_mfma_f32_16x16x32_bf16 v[24:27], v[180:183], v[198:201], v[24:27]
	v_mfma_f32_16x16x32_bf16 v[16:19], v[172:175], v[206:209], v[16:19]
	v_mfma_f32_16x16x32_bf16 v[8:11], v[180:183], v[206:209], v[8:11]
	v_mfma_f32_16x16x32_bf16 v[4:7], v[172:175], v[214:217], v[4:7]
	v_mfma_f32_16x16x32_bf16 v[0:3], v[180:183], v[214:217], v[0:3]
	s_barrier
	s_add_i32 s33, 0, 0x18000
	s_add_i32 s46, 0, 0x1c000
	v_add_u32_e32 v164, s33, v147
	v_add_u32_e32 v180, s46, v147
	ds_read_b128 v[152:155], v164
	ds_read_b128 v[156:159], v164 offset:1024
	ds_read_b128 v[160:163], v164 offset:2048
	ds_read_b128 v[164:167], v164 offset:3072
	ds_read_b128 v[168:171], v180
	ds_read_b128 v[172:175], v180 offset:1024
	ds_read_b128 v[176:179], v180 offset:2048
	ds_read_b128 v[180:183], v180 offset:3072
	s_add_u32 s28, s54, 0x4000
	s_addc_u32 s29, s55, 0
	s_mov_b32 m0, s61
	v_lshl_add_u64 v[224:225], s[28:29], 0, v[128:129]
	ds_read_b128 v[184:187], v151 offset:32768
	ds_read_b128 v[190:193], v151 offset:33792
	ds_read_b128 v[194:197], v151 offset:34816
	ds_read_b128 v[198:201], v151 offset:35840
	ds_read_b128 v[202:205], v151 offset:36864
	ds_read_b128 v[206:209], v151 offset:37888
	ds_read_b128 v[210:213], v151 offset:38912
	ds_read_b128 v[214:217], v151 offset:39936
	global_load_lds_dwordx4 v[224:225], off
	v_lshl_add_u64 v[224:225], s[28:29], 0, v[132:133]
	s_mov_b32 m0, s62
	s_nop 0
	global_load_lds_dwordx4 v[224:225], off
	s_waitcnt vmcnt(8)
	s_waitcnt lgkmcnt(0)
	s_nop 0
	s_barrier
	s_waitcnt lgkmcnt(0)
	v_mfma_f32_16x16x32_bf16 v[124:127], v[152:155], v[184:187], v[124:127]
	v_mfma_f32_16x16x32_bf16 v[120:123], v[160:163], v[184:187], v[120:123]
	v_mfma_f32_16x16x32_bf16 v[116:119], v[152:155], v[194:197], v[116:119]
	v_mfma_f32_16x16x32_bf16 v[108:111], v[160:163], v[194:197], v[108:111]
	v_mfma_f32_16x16x32_bf16 v[100:103], v[152:155], v[202:205], v[100:103]
	v_mfma_f32_16x16x32_bf16 v[92:95], v[160:163], v[202:205], v[92:95]
	v_mfma_f32_16x16x32_bf16 v[84:87], v[152:155], v[210:213], v[84:87]
	v_mfma_f32_16x16x32_bf16 v[76:79], v[160:163], v[210:213], v[76:79]
	v_mfma_f32_16x16x32_bf16 v[124:127], v[156:159], v[190:193], v[124:127]
	v_mfma_f32_16x16x32_bf16 v[120:123], v[164:167], v[190:193], v[120:123]
	v_mfma_f32_16x16x32_bf16 v[116:119], v[156:159], v[198:201], v[116:119]
	v_mfma_f32_16x16x32_bf16 v[108:111], v[164:167], v[198:201], v[108:111]
	v_mfma_f32_16x16x32_bf16 v[100:103], v[156:159], v[206:209], v[100:103]
	v_mfma_f32_16x16x32_bf16 v[92:95], v[164:167], v[206:209], v[92:95]
	v_mfma_f32_16x16x32_bf16 v[84:87], v[156:159], v[214:217], v[84:87]
	v_mfma_f32_16x16x32_bf16 v[76:79], v[164:167], v[214:217], v[76:79]
	v_mfma_f32_16x16x32_bf16 v[112:115], v[168:171], v[184:187], v[112:115]
	v_mfma_f32_16x16x32_bf16 v[104:107], v[176:179], v[184:187], v[104:107]
	v_mfma_f32_16x16x32_bf16 v[96:99], v[168:171], v[194:197], v[96:99]
	v_mfma_f32_16x16x32_bf16 v[88:91], v[176:179], v[194:197], v[88:91]
	v_mfma_f32_16x16x32_bf16 v[80:83], v[168:171], v[202:205], v[80:83]
	v_mfma_f32_16x16x32_bf16 v[72:75], v[176:179], v[202:205], v[72:75]
	v_mfma_f32_16x16x32_bf16 v[68:71], v[168:171], v[210:213], v[68:71]
	v_mfma_f32_16x16x32_bf16 v[64:67], v[176:179], v[210:213], v[64:67]
	v_mfma_f32_16x16x32_bf16 v[112:115], v[172:175], v[190:193], v[112:115]
	v_mfma_f32_16x16x32_bf16 v[104:107], v[180:183], v[190:193], v[104:107]
	v_mfma_f32_16x16x32_bf16 v[96:99], v[172:175], v[198:201], v[96:99]
	v_mfma_f32_16x16x32_bf16 v[88:91], v[180:183], v[198:201], v[88:91]
	v_mfma_f32_16x16x32_bf16 v[80:83], v[172:175], v[206:209], v[80:83]
	v_mfma_f32_16x16x32_bf16 v[72:75], v[180:183], v[206:209], v[72:75]
	v_mfma_f32_16x16x32_bf16 v[68:71], v[172:175], v[214:217], v[68:71]
	v_mfma_f32_16x16x32_bf16 v[64:67], v[180:183], v[214:217], v[64:67]
	s_barrier
	v_lshl_add_u64 v[144:145], v[220:221], 0, s[92:93]
	s_mov_b32 m0, s64
	s_nop 0
	global_load_lds_dwordx4 v[144:145], off
	v_lshl_add_u64 v[144:145], v[222:223], 0, s[92:93]
	s_mov_b32 m0, s65
	s_nop 0
	global_load_lds_dwordx4 v[144:145], off
	ds_read_b128 v[184:187], v151 offset:49152
	ds_read_b128 v[190:193], v151 offset:50176
	ds_read_b128 v[194:197], v151 offset:51200
	ds_read_b128 v[198:201], v151 offset:52224
	ds_read_b128 v[202:205], v151 offset:53248
	ds_read_b128 v[206:209], v151 offset:54272
	ds_read_b128 v[210:213], v151 offset:55296
	ds_read_b128 v[214:217], v151 offset:56320
	s_add_i32 s28, s33, s34
	s_add_u32 s56, s52, 0x80
	s_addc_u32 s57, s53, 0
	v_lshl_add_u64 v[144:145], s[56:57], 0, v[130:131]
	s_mov_b32 m0, s28
	s_nop 0
	global_load_lds_dwordx4 v[144:145], off
	v_lshl_add_u64 v[144:145], s[56:57], 0, v[134:135]
	s_add_i32 m0, s28, 0x2000
	s_nop 0
	global_load_lds_dwordx4 v[144:145], off
	s_add_u32 s28, s52, 0xb0080
	s_addc_u32 s29, s53, 0
	s_add_i32 s33, s46, s34
	v_lshl_add_u64 v[144:145], s[28:29], 0, v[130:131]
	s_mov_b32 m0, s33
	s_nop 0
	global_load_lds_dwordx4 v[144:145], off
	v_lshl_add_u64 v[144:145], s[28:29], 0, v[134:135]
	s_add_i32 m0, s33, 0x2000
	s_nop 0
	global_load_lds_dwordx4 v[144:145], off
	s_waitcnt vmcnt(8)
	s_waitcnt lgkmcnt(0)
	s_nop 0
	s_barrier
	s_waitcnt lgkmcnt(0)
	v_mfma_f32_16x16x32_bf16 v[60:63], v[152:155], v[184:187], v[60:63]
	v_mfma_f32_16x16x32_bf16 v[56:59], v[160:163], v[184:187], v[56:59]
	v_mfma_f32_16x16x32_bf16 v[52:55], v[152:155], v[194:197], v[52:55]
	v_mfma_f32_16x16x32_bf16 v[44:47], v[160:163], v[194:197], v[44:47]
	v_mfma_f32_16x16x32_bf16 v[36:39], v[152:155], v[202:205], v[36:39]
	v_mfma_f32_16x16x32_bf16 v[28:31], v[160:163], v[202:205], v[28:31]
	v_mfma_f32_16x16x32_bf16 v[20:23], v[152:155], v[210:213], v[20:23]
	v_mfma_f32_16x16x32_bf16 v[12:15], v[160:163], v[210:213], v[12:15]
	v_mfma_f32_16x16x32_bf16 v[60:63], v[156:159], v[190:193], v[60:63]
	v_mfma_f32_16x16x32_bf16 v[56:59], v[164:167], v[190:193], v[56:59]
	v_mfma_f32_16x16x32_bf16 v[52:55], v[156:159], v[198:201], v[52:55]
	v_mfma_f32_16x16x32_bf16 v[44:47], v[164:167], v[198:201], v[44:47]
	v_mfma_f32_16x16x32_bf16 v[36:39], v[156:159], v[206:209], v[36:39]
	v_mfma_f32_16x16x32_bf16 v[28:31], v[164:167], v[206:209], v[28:31]
	v_mfma_f32_16x16x32_bf16 v[20:23], v[156:159], v[214:217], v[20:23]
	v_mfma_f32_16x16x32_bf16 v[12:15], v[164:167], v[214:217], v[12:15]
	v_mfma_f32_16x16x32_bf16 v[48:51], v[168:171], v[184:187], v[48:51]
	v_mfma_f32_16x16x32_bf16 v[40:43], v[176:179], v[184:187], v[40:43]
	v_mfma_f32_16x16x32_bf16 v[32:35], v[168:171], v[194:197], v[32:35]
	v_mfma_f32_16x16x32_bf16 v[24:27], v[176:179], v[194:197], v[24:27]
	v_mfma_f32_16x16x32_bf16 v[16:19], v[168:171], v[202:205], v[16:19]
	v_mfma_f32_16x16x32_bf16 v[8:11], v[176:179], v[202:205], v[8:11]
	v_mfma_f32_16x16x32_bf16 v[4:7], v[168:171], v[210:213], v[4:7]
	v_mfma_f32_16x16x32_bf16 v[0:3], v[176:179], v[210:213], v[0:3]
	v_mfma_f32_16x16x32_bf16 v[48:51], v[172:175], v[190:193], v[48:51]
	v_mfma_f32_16x16x32_bf16 v[40:43], v[180:183], v[190:193], v[40:43]
	v_mfma_f32_16x16x32_bf16 v[32:35], v[172:175], v[198:201], v[32:35]
	v_mfma_f32_16x16x32_bf16 v[24:27], v[180:183], v[198:201], v[24:27]
	v_mfma_f32_16x16x32_bf16 v[16:19], v[172:175], v[206:209], v[16:19]
	v_mfma_f32_16x16x32_bf16 v[8:11], v[180:183], v[206:209], v[8:11]
	v_mfma_f32_16x16x32_bf16 v[4:7], v[172:175], v[214:217], v[4:7]
	v_mfma_f32_16x16x32_bf16 v[0:3], v[180:183], v[214:217], v[0:3]
	s_barrier
	s_add_i32 s91, s91, 2
	s_add_u32 s89, s89, 0x100
	s_addc_u32 s90, s90, 0
	s_cmp_gt_u32 s91, 41
	s_mov_b64 s[46:47], s[50:51]
	s_cbranch_scc0 .LBB0_325
	s_and_b64 vcc, exec, s[10:11]
	s_cbranch_vccz .LBB0_328
	s_barrier
